# final-norm pipelined + FFN2 tile order WGM4 + attention shift via MFMA C-init (no ones MFMA) + deferred l combine
# speedup vs baseline: 1.0113x; 1.0104x over previous
.LBB0_338:
	s_or_b64 exec, exec, s[12:13]
	v_mov_b32_e32 v51, s43
	v_mov_b32_e32 v56, s42
	v_cmp_gt_i32_e64 s[12:13], 0, v185
	s_nop 1
	v_max_f32_e32 v57, v18, v18
	v_mov_b32_e32 v190, 0
	v_cndmask_b32_e64 v51, v51, v56, s[12:13]
	v_cndmask_b32_e64 v56, v51, 0, s[8:9]
	v_max_f32_e32 v51, v19, v19
	v_max_f32_e32 v51, v57, v51
	v_max3_f32 v51, v51, v20, v21
	v_max3_f32 v51, v51, v22, v23
	v_max3_f32 v51, v51, v24, v25
	v_max3_f32 v51, v51, v26, v27
	v_max3_f32 v51, v51, v28, v29
	v_max3_f32 v51, v51, v30, v31
	v_max3_f32 v51, v51, v32, v33
	v_max3_f32 v51, v51, v2, v3
	v_max3_f32 v51, v51, v4, v5
	v_max3_f32 v51, v51, v6, v7
	v_max3_f32 v51, v51, v8, v9
	v_max3_f32 v51, v51, v10, v11
	v_max3_f32 v51, v51, v12, v13
	v_max3_f32 v51, v51, v14, v15
	v_max3_f32 v51, v51, v16, v17
	v_mov_b32_e32 v57, v51
	s_nop 1
	v_permlane32_swap_b32_e32 v51, v57
	v_max_f32_e32 v57, v57, v57
	v_max_f32_e32 v51, v51, v51
	v_max_f32_e32 v51, v51, v57
	v_add_f32_e32 v57, v56, v51
	v_sub_f32_e32 v191, s43, v57
	v_sub_f32_e32 v190, 0, v57
	v_sub_f32_e32 v192, s42, v57
	v_mov_b32_e32 v176, 0
	v_readfirstlane_b32 s98, v185
	s_mov_b32 s99, 64
	v_sub_f32_e32 v56, v56, v57
	v_add_f32_e32 v3, v3, v56
	v_add_f32_e32 v2, v2, v56
	v_add_f32_e32 v4, v4, v56
	v_exp_f32_e32 v196, v3
	v_lshlrev_b32_e32 v3, 4, v55
	s_xor_b64 s[42:43], s[2:3], -1
	v_exp_f32_e32 v195, v2
	v_exp_f32_e32 v197, v4
	v_lshlrev_b32_e32 v2, 3, v55
	v_and_b32_e32 v3, 0xc0, v3
	v_lshlrev_b32_e32 v4, 1, v55
	v_and_or_b32 v3, v2, 24, v3
	v_and_b32_e32 v4, 32, v4
	v_and_b32_e32 v2, 0x100, v2
	s_cmp_lg_u32 0, -1
	v_or3_b32 v2, v3, v4, v2
	s_cselect_b32 s2, 0, 0
	v_add_u32_e32 v180, s2, v2
	s_addk_i32 s2, 0x4000
	v_add_u32_e32 v177, s2, v2
	v_add_lshl_u32 v2, v185, v53, 2
	v_ashrrev_i32_e32 v51, 31, v50
	v_add_f32_e32 v18, v18, v56
	v_add_f32_e32 v19, v19, v56
	v_add_f32_e32 v20, v20, v56
	v_add_f32_e32 v21, v21, v56
	v_add_f32_e32 v22, v22, v56
	v_add_f32_e32 v23, v23, v56
	v_add_f32_e32 v24, v24, v56
	v_add_f32_e32 v25, v25, v56
	v_add_f32_e32 v26, v26, v56
	v_add_f32_e32 v27, v27, v56
	v_add_f32_e32 v28, v28, v56
	v_add_f32_e32 v29, v29, v56
	v_add_f32_e32 v30, v30, v56
	v_add_f32_e32 v31, v31, v56
	v_add_f32_e32 v32, v32, v56
	v_add_f32_e32 v33, v33, v56
	v_add_f32_e32 v5, v5, v56
	v_add_f32_e32 v6, v6, v56
	v_add_f32_e32 v7, v7, v56
	v_add_f32_e32 v8, v8, v56
	v_add_f32_e32 v9, v9, v56
	v_add_f32_e32 v10, v10, v56
	v_add_f32_e32 v11, v11, v56
	v_add_f32_e32 v12, v12, v56
	v_add_f32_e32 v13, v13, v56
	v_add_f32_e32 v14, v14, v56
	v_add_f32_e32 v15, v15, v56
	v_add_f32_e32 v16, v16, v56
	v_add_f32_e32 v17, v17, v56
	v_sub_u32_e32 v2, v98, v2
	s_add_i32 s2, 0, 0x10c80
	v_exp_f32_e32 v199, v18
	v_exp_f32_e32 v201, v19
	v_exp_f32_e32 v202, v20
	v_exp_f32_e32 v205, v21
	v_exp_f32_e32 v207, v22
	v_exp_f32_e32 v209, v23
	v_exp_f32_e32 v211, v24
	v_exp_f32_e32 v213, v25
	v_exp_f32_e32 v215, v26
	v_exp_f32_e32 v216, v27
	v_exp_f32_e32 v217, v28
	v_exp_f32_e32 v218, v29
	v_exp_f32_e32 v221, v30
	v_exp_f32_e32 v222, v31
	v_exp_f32_e32 v223, v32
	v_exp_f32_e32 v224, v33
	v_exp_f32_e32 v198, v5
	v_exp_f32_e32 v200, v6
	v_exp_f32_e32 v203, v7
	v_exp_f32_e32 v204, v8
	v_exp_f32_e32 v206, v9
	v_exp_f32_e32 v208, v10
	v_exp_f32_e32 v210, v11
	v_exp_f32_e32 v212, v12
	v_exp_f32_e32 v214, v13
	v_exp_f32_e32 v150, v14
	v_exp_f32_e32 v151, v15
	v_exp_f32_e32 v152, v16
	v_exp_f32_e32 v153, v17
	v_add_u32_e32 v194, s2, v2
	v_lshl_add_u64 v[2:3], s[30:31], 0, v[50:51]
	s_waitcnt vmcnt(0)
	v_mad_u64_u32 v[4:5], s[2:3], v2, s49, 0
	v_and_b32_e32 v2, 15, v52
	v_mad_i32_i24 v3, v3, s49, v5
	v_lshl_or_b32 v2, v2, 4, v4
	s_mov_b32 s82, 0
	s_waitcnt vmcnt(3)
	ds_write_b128 v183, v[34:37] offset:16384
	s_waitcnt vmcnt(2)
	ds_write_b128 v184, v[38:41] offset:16384
	s_waitcnt vmcnt(1)
	ds_write_b128 v181, v[42:45] offset:49152
	s_waitcnt vmcnt(0)
	ds_write_b128 v182, v[46:49] offset:49152
	v_sub_u32_e32 v193, s81, v54
	s_mov_b32 s83, 2
	v_lshl_add_u64 v[160:161], s[40:41], 0, v[2:3]
	v_mov_b32_e32 v2, 0
	v_mov_b32_e32 v3, v176
	v_mov_b32_e32 v4, v176
	v_mov_b32_e32 v5, v176
	v_mov_b32_e32 v6, v176
	v_mov_b32_e32 v7, v176
	v_mov_b32_e32 v8, v176
	v_mov_b32_e32 v9, v176
	v_mov_b32_e32 v10, v176
	v_mov_b32_e32 v11, v176
	v_mov_b32_e32 v12, v176
	v_mov_b32_e32 v13, v176
	v_mov_b32_e32 v14, v176
	v_mov_b32_e32 v15, v176
	v_mov_b32_e32 v16, v176
	v_mov_b32_e32 v17, v176
	v_mov_b32_e32 v18, 0
	v_mov_b32_e32 v19, v176
	v_mov_b32_e32 v20, v176
	v_mov_b32_e32 v21, v176
	v_mov_b32_e32 v22, v176
	v_mov_b32_e32 v23, v176
	v_mov_b32_e32 v24, v176
	v_mov_b32_e32 v25, v176
	v_mov_b32_e32 v26, v176
	v_mov_b32_e32 v27, v176
	v_mov_b32_e32 v28, v176
	v_mov_b32_e32 v29, v176
	v_mov_b32_e32 v30, v176
	v_mov_b32_e32 v31, v176
	v_mov_b32_e32 v32, v176
	v_mov_b32_e32 v33, v176
	v_mov_b32_e32 v34, 0
	v_mov_b32_e32 v35, v176
	v_mov_b32_e32 v36, v176
	v_mov_b32_e32 v37, v176
	v_mov_b32_e32 v38, v176
	v_mov_b32_e32 v39, v176
	v_mov_b32_e32 v40, v176
	v_mov_b32_e32 v41, v176
	v_mov_b32_e32 v42, v176
	v_mov_b32_e32 v43, v176
	v_mov_b32_e32 v44, v176
	v_mov_b32_e32 v45, v176
	v_mov_b32_e32 v46, v176
	v_mov_b32_e32 v47, v176
	v_mov_b32_e32 v48, v176
	v_mov_b32_e32 v49, v176
	v_mov_b32_e32 v50, 0
	v_mov_b32_e32 v51, v176
	v_mov_b32_e32 v52, v176
	v_mov_b32_e32 v53, v176
	v_mov_b32_e32 v54, v176
	v_mov_b32_e32 v55, v176
	v_mov_b32_e32 v56, v176
	v_mov_b32_e32 v57, v176
	v_mov_b32_e32 v58, v176
	v_mov_b32_e32 v59, v176
	v_mov_b32_e32 v60, v176
	v_mov_b32_e32 v61, v176
	v_mov_b32_e32 v62, v176
	v_mov_b32_e32 v63, v176
	v_mov_b32_e32 v64, v176
	v_mov_b32_e32 v65, v176
	s_waitcnt lgkmcnt(0)
	s_barrier
	s_branch .LBB0_346
.LBB0_345:
	s_or_b64 exec, exec, s[2:3]
	v_add_f32_e32 v176, v176, v219
	ds_read_b64_tr_b16 v[196:197], v177 offset:0
	ds_read_b64_tr_b16 v[198:199], v177 offset:0x800
	ds_read_b64_tr_b16 v[200:201], v177 offset:0x1000
	ds_read_b64_tr_b16 v[202:203], v177 offset:0x1800
	ds_read_b64_tr_b16 v[206:207], v177 offset:0x2000
	ds_read_b64_tr_b16 v[208:209], v177 offset:0x2800
	ds_read_b64_tr_b16 v[210:211], v177 offset:0x3000
	ds_read_b64_tr_b16 v[212:213], v177 offset:0x3800
	s_waitcnt lgkmcnt(0)
	v_add_f32_e32 v176, v176, v98
	v_mfma_f32_32x32x16_bf16 v[50:65], v[150:153], v[196:199], v[50:65]
	v_exp_f32_e32 v195, v66
	v_exp_f32_e32 v196, v67
	ds_read_b64_tr_b16 v[66:67], v177 offset:0x200
	v_exp_f32_e32 v197, v68
	v_exp_f32_e32 v198, v69
	ds_read_b64_tr_b16 v[68:69], v177 offset:0xa00
	v_exp_f32_e32 v199, v82
	v_mfma_f32_32x32x16_bf16 v[50:65], v[134:137], v[200:203], v[50:65]
	v_exp_f32_e32 v201, v83
	ds_read_b64_tr_b16 v[82:83], v177 offset:0x1200
	v_exp_f32_e32 v202, v84
	v_exp_f32_e32 v205, v85
	ds_read_b64_tr_b16 v[84:85], v177 offset:0x1a00
	ds_read_b64_tr_b16 v[214:215], v177 offset:0x2200
	ds_read_b64_tr_b16 v[216:217], v177 offset:0x2a00
	v_mfma_f32_32x32x16_bf16 v[50:65], v[130:133], v[206:209], v[50:65]
	ds_read_b64_tr_b16 v[218:219], v177 offset:0x3200
	ds_read_b64_tr_b16 v[220:221], v177 offset:0x3a00
	s_waitcnt lgkmcnt(0)
	v_mfma_f32_32x32x16_bf16 v[50:65], v[126:129], v[210:213], v[50:65]
	v_mfma_f32_32x32x16_bf16 v[34:49], v[150:153], v[66:69], v[34:49]
	ds_read_b64_tr_b16 v[66:67], v177 offset:0x400
	ds_read_b64_tr_b16 v[68:69], v177 offset:0xc00
	v_exp_f32_e32 v200, v70
	v_exp_f32_e32 v203, v71
	ds_read_b64_tr_b16 v[70:71], v177 offset:0x1400
	v_exp_f32_e32 v204, v72
	v_exp_f32_e32 v206, v73
	v_mfma_f32_32x32x16_bf16 v[34:49], v[134:137], v[82:85], v[34:49]
	ds_read_b64_tr_b16 v[72:73], v177 offset:0x1c00
	ds_read_b64_tr_b16 v[82:83], v177 offset:0x2400
	ds_read_b64_tr_b16 v[84:85], v177 offset:0x2c00
	v_exp_f32_e32 v207, v86
	v_exp_f32_e32 v209, v87
	ds_read_b64_tr_b16 v[86:87], v177 offset:0x3400
	v_exp_f32_e32 v211, v88
	v_mfma_f32_32x32x16_bf16 v[34:49], v[130:133], v[214:217], v[34:49]
	v_exp_f32_e32 v213, v89
	ds_read_b64_tr_b16 v[88:89], v177 offset:0x3c00
	s_waitcnt lgkmcnt(0)
	v_mfma_f32_32x32x16_bf16 v[34:49], v[126:129], v[218:221], v[34:49]
	v_mfma_f32_32x32x16_bf16 v[18:33], v[150:153], v[66:69], v[18:33]
	ds_read_b64_tr_b16 v[66:67], v177 offset:0x600
	ds_read_b64_tr_b16 v[68:69], v177 offset:0xe00
	v_exp_f32_e32 v208, v74
	v_exp_f32_e32 v210, v75
	v_exp_f32_e32 v212, v76
	v_exp_f32_e32 v214, v77
	v_exp_f32_e32 v215, v90
	v_mfma_f32_32x32x16_bf16 v[18:33], v[134:137], v[70:73], v[18:33]
	ds_read_b64_tr_b16 v[70:71], v177 offset:0x1600
	ds_read_b64_tr_b16 v[72:73], v177 offset:0x1e00
	ds_read_b64_tr_b16 v[74:75], v177 offset:0x2600
	ds_read_b64_tr_b16 v[76:77], v177 offset:0x2e00
	v_exp_f32_e32 v216, v91
	v_exp_f32_e32 v217, v92
	v_exp_f32_e32 v218, v93
	v_mfma_f32_32x32x16_bf16 v[18:33], v[130:133], v[82:85], v[18:33]
	ds_read_b64_tr_b16 v[82:83], v177 offset:0x3600
	ds_read_b64_tr_b16 v[84:85], v177 offset:0x3e00
	s_waitcnt lgkmcnt(0)
	v_mfma_f32_32x32x16_bf16 v[18:33], v[126:129], v[86:89], v[18:33]
	v_mfma_f32_32x32x16_bf16 v[2:17], v[150:153], v[66:69], v[2:17]
	v_exp_f32_e32 v221, v94
	v_exp_f32_e32 v150, v78
	v_exp_f32_e32 v222, v95
	v_exp_f32_e32 v151, v79
	v_exp_f32_e32 v223, v96
	v_exp_f32_e32 v152, v80
	v_exp_f32_e32 v224, v97
	v_mfma_f32_32x32x16_bf16 v[2:17], v[134:137], v[70:73], v[2:17]
	v_exp_f32_e32 v153, v81
	s_barrier
	s_waitcnt vmcnt(0)
	s_add_i32 s83, s83, 2
	v_add_u32_e32 v194, 0x200, v194
	v_mfma_f32_32x32x16_bf16 v[2:17], v[130:133], v[74:77], v[2:17]
	v_lshl_add_u64 v[160:161], v[160:161], 0, s[26:27]
	s_cmp_ge_u32 s83, s78
	s_waitcnt vmcnt(3)
	ds_write_b128 v183, v[138:141] offset:16384
	s_waitcnt vmcnt(1)
	ds_write_b128 v184, v[154:157] offset:16384
	ds_write_b128 v181, v[142:145] offset:49152
	s_waitcnt vmcnt(0)
	ds_write_b128 v182, v[146:149] offset:49152
	s_waitcnt lgkmcnt(0)
	s_barrier
	v_mfma_f32_32x32x16_bf16 v[2:17], v[126:129], v[82:85], v[2:17]
	s_cbranch_scc1 .LBB0_350
.LBB0_346:
	s_add_i32 s100, s82, 64
	s_cmp_eq_u32 s100, s99
	s_cbranch_scc1 .Lattn_refill_a
.Lattn_back_a:
	ds_read_b128 v[126:129], v186 offset:49152
	ds_read_b128 v[130:133], v186 offset:57344
	v_add_f32_e32 v98, 0, v199
	v_add_f32_e32 v98, v201, v98
	v_add_f32_e32 v98, v202, v98
	v_add_f32_e32 v98, v205, v98
	v_add_f32_e32 v98, v207, v98
	v_add_f32_e32 v98, v209, v98
	s_waitcnt lgkmcnt(1)
	v_mfma_f32_32x32x16_bf16 v[82:97], v[126:129], v[118:121], v[236:251]
	v_add_f32_e32 v98, v211, v98
	v_add_f32_e32 v98, v213, v98
	v_add_f32_e32 v98, v215, v98
	ds_read_b128 v[134:137], v187 offset:49152
	ds_read_b128 v[138:141], v187 offset:57344
	ds_read_b128 v[142:145], v188 offset:49152
	ds_read_b128 v[146:149], v188 offset:57344
	ds_read_b128 v[154:157], v189 offset:49152
	ds_read_b128 v[226:229], v189 offset:57344
	v_add_f32_e32 v98, v216, v98
	v_add_f32_e32 v98, v217, v98
	v_add_f32_e32 v98, v218, v98
	s_waitcnt lgkmcnt(6)
	v_mfma_f32_32x32x16_bf16 v[66:81], v[130:133], v[118:121], v[236:251]
	v_add_f32_e32 v98, v221, v98
	v_add_f32_e32 v98, v222, v98
	v_add_f32_e32 v98, v223, v98
	v_add_f32_e32 v98, v224, v98
	v_add_f32_e32 v98, v195, v98
	v_add_f32_e32 v98, v196, v98
	v_add_f32_e32 v98, v197, v98
	s_waitcnt lgkmcnt(5)
	v_mfma_f32_32x32x16_bf16 v[82:97], v[134:137], v[114:117], v[82:97]
	v_add_f32_e32 v98, v198, v98
	v_add_f32_e32 v98, v200, v98
	v_add_f32_e32 v98, v203, v98
	v_add_f32_e32 v98, v204, v98
	v_add_f32_e32 v98, v206, v98
	v_add_f32_e32 v98, v208, v98
	v_add_f32_e32 v98, v210, v98
	s_waitcnt lgkmcnt(4)
	v_mfma_f32_32x32x16_bf16 v[66:81], v[138:141], v[114:117], v[66:81]
	v_add_f32_e32 v98, v212, v98
	v_add_f32_e32 v98, v214, v98
	v_add_f32_e32 v98, v150, v98
	v_add_f32_e32 v98, v151, v98
	v_add_f32_e32 v98, v152, v98
	v_add_f32_e32 v219, v153, v98
	s_waitcnt lgkmcnt(3)
	v_mfma_f32_32x32x16_bf16 v[82:97], v[142:145], v[110:113], v[82:97]
	v_cvt_pk_bf16_f32 v134, v199, v201
	v_cvt_pk_bf16_f32 v135, v202, v205
	v_cvt_pk_bf16_f32 v136, v207, v209
	v_cvt_pk_bf16_f32 v137, v211, v213
	v_cvt_pk_bf16_f32 v138, v215, v216
	s_waitcnt lgkmcnt(2)
	v_mfma_f32_32x32x16_bf16 v[66:81], v[146:149], v[110:113], v[66:81]
	v_cvt_pk_bf16_f32 v139, v217, v218
	v_cvt_pk_bf16_f32 v140, v221, v222
	v_cvt_pk_bf16_f32 v141, v223, v224
	v_cvt_pk_bf16_f32 v126, v195, v196
	v_cvt_pk_bf16_f32 v127, v197, v198
	v_cvt_pk_bf16_f32 v128, v200, v203
	v_cvt_pk_bf16_f32 v129, v204, v206
	s_waitcnt lgkmcnt(1)
	v_mfma_f32_32x32x16_bf16 v[82:97], v[154:157], v[106:109], v[82:97]
	v_cvt_pk_bf16_f32 v130, v208, v210
	v_cvt_pk_bf16_f32 v131, v212, v214
	v_cvt_pk_bf16_f32 v132, v150, v151
	v_cvt_pk_bf16_f32 v133, v152, v153
	s_waitcnt lgkmcnt(0)
	v_mfma_f32_32x32x16_bf16 v[66:81], v[226:229], v[106:109], v[66:81]
	v_add_co_u32_e32 v150, vcc, 0x50000, v160
	s_nop 1
	v_addc_co_u32_e32 v151, vcc, 0, v161, vcc
	global_load_dwordx4 v[142:145], v[160:161], off offset:2048
	global_load_dwordx4 v[146:149], v[160:161], off
	global_load_dwordx4 v[154:157], v[150:151], off offset:2048
	s_nop 0
	global_load_dwordx4 v[150:153], v[150:151], off
	s_and_saveexec_b64 s[2:3], s[8:9]
	s_cbranch_execz .LBB0_348
	ds_read2_b32 v[196:197], v194 offset1:1
	ds_read2_b32 v[198:199], v194 offset0:16 offset1:17
	ds_read2_b32 v[200:201], v194 offset0:18 offset1:19
	ds_read2_b32 v[202:203], v194 offset0:24 offset1:25
	ds_read2_b32 v[204:205], v194 offset0:26 offset1:27
	ds_read2_b32 v[206:207], v194 offset0:2 offset1:3
	ds_read2_b32 v[208:209], v194 offset0:8 offset1:9
	ds_read2_b32 v[210:211], v194 offset0:10 offset1:11
	s_waitcnt lgkmcnt(7)
	v_pk_add_f32 v[82:83], v[82:83], v[196:197]
	s_waitcnt lgkmcnt(3)
	v_pk_add_f32 v[96:97], v[96:97], v[204:205]
	v_pk_add_f32 v[94:95], v[94:95], v[202:203]
	v_pk_add_f32 v[92:93], v[92:93], v[200:201]
	v_pk_add_f32 v[90:91], v[90:91], v[198:199]
	s_waitcnt lgkmcnt(0)
	v_pk_add_f32 v[88:89], v[88:89], v[210:211]
	v_pk_add_f32 v[86:87], v[86:87], v[208:209]
	v_pk_add_f32 v[84:85], v[84:85], v[206:207]
	ds_read2_b32 v[196:197], v194 offset0:48 offset1:49
	ds_read2_b32 v[198:199], v194 offset0:50 offset1:51
	ds_read2_b32 v[200:201], v194 offset0:56 offset1:57
	ds_read2_b32 v[202:203], v194 offset0:58 offset1:59
	ds_read2_b32 v[204:205], v194 offset0:32 offset1:33
	ds_read2_b32 v[206:207], v194 offset0:34 offset1:35
	ds_read2_b32 v[208:209], v194 offset0:40 offset1:41
	ds_read2_b32 v[210:211], v194 offset0:42 offset1:43
	s_waitcnt lgkmcnt(4)
	v_pk_add_f32 v[80:81], v[80:81], v[202:203]
	v_pk_add_f32 v[78:79], v[78:79], v[200:201]
	v_pk_add_f32 v[76:77], v[76:77], v[198:199]
	v_pk_add_f32 v[74:75], v[74:75], v[196:197]
	s_waitcnt lgkmcnt(0)
	v_pk_add_f32 v[72:73], v[72:73], v[210:211]
	v_pk_add_f32 v[70:71], v[70:71], v[208:209]
	v_pk_add_f32 v[68:69], v[68:69], v[206:207]
	v_pk_add_f32 v[66:67], v[66:67], v[204:205]
.LBB0_348:
	s_or_b64 exec, exec, s[2:3]
	ds_read_b64_tr_b16 v[196:197], v180 offset:0
	ds_read_b64_tr_b16 v[198:199], v180 offset:0x800
	ds_read_b64_tr_b16 v[200:201], v180 offset:0x1000
	ds_read_b64_tr_b16 v[202:203], v180 offset:0x1800
	ds_read_b64_tr_b16 v[204:205], v180 offset:0x2000
	ds_read_b64_tr_b16 v[206:207], v180 offset:0x2800
	ds_read_b64_tr_b16 v[208:209], v180 offset:0x3000
	ds_read_b64_tr_b16 v[210:211], v180 offset:0x3800
	s_waitcnt lgkmcnt(0)
	s_addk_i32 s82, 0x80
	v_mfma_f32_32x32x16_bf16 v[50:65], v[134:137], v[196:199], v[50:65]
	v_exp_f32_e32 v213, v66
	v_exp_f32_e32 v215, v67
	ds_read_b64_tr_b16 v[66:67], v180 offset:0x200
	v_exp_f32_e32 v217, v68
	v_exp_f32_e32 v221, v69
	ds_read_b64_tr_b16 v[68:69], v180 offset:0xa00
	v_exp_f32_e32 v212, v82
	v_mfma_f32_32x32x16_bf16 v[50:65], v[138:141], v[200:203], v[50:65]
	v_exp_f32_e32 v214, v83
	ds_read_b64_tr_b16 v[82:83], v180 offset:0x1200
	v_exp_f32_e32 v216, v84
	v_exp_f32_e32 v218, v85
	ds_read_b64_tr_b16 v[84:85], v180 offset:0x1a00
	ds_read_b64_tr_b16 v[196:197], v180 offset:0x2200
	ds_read_b64_tr_b16 v[198:199], v180 offset:0x2a00
	v_mfma_f32_32x32x16_bf16 v[50:65], v[126:129], v[204:207], v[50:65]
	ds_read_b64_tr_b16 v[200:201], v180 offset:0x3200
	ds_read_b64_tr_b16 v[202:203], v180 offset:0x3a00
	s_waitcnt lgkmcnt(0)
	v_mfma_f32_32x32x16_bf16 v[50:65], v[130:133], v[208:211], v[50:65]
	v_mfma_f32_32x32x16_bf16 v[34:49], v[134:137], v[66:69], v[34:49]
	ds_read_b64_tr_b16 v[66:67], v180 offset:0x400
	ds_read_b64_tr_b16 v[68:69], v180 offset:0xc00
	v_exp_f32_e32 v205, v70
	v_exp_f32_e32 v207, v71
	ds_read_b64_tr_b16 v[70:71], v180 offset:0x1400
	v_exp_f32_e32 v209, v72
	v_exp_f32_e32 v211, v73
	v_mfma_f32_32x32x16_bf16 v[34:49], v[138:141], v[82:85], v[34:49]
	ds_read_b64_tr_b16 v[72:73], v180 offset:0x1c00
	ds_read_b64_tr_b16 v[82:83], v180 offset:0x2400
	ds_read_b64_tr_b16 v[84:85], v180 offset:0x2c00
	v_exp_f32_e32 v204, v86
	v_exp_f32_e32 v206, v87
	ds_read_b64_tr_b16 v[86:87], v180 offset:0x3400
	v_exp_f32_e32 v208, v88
	v_mfma_f32_32x32x16_bf16 v[34:49], v[126:129], v[196:199], v[34:49]
	v_exp_f32_e32 v210, v89
	ds_read_b64_tr_b16 v[88:89], v180 offset:0x3c00
	s_waitcnt lgkmcnt(0)
	v_mfma_f32_32x32x16_bf16 v[34:49], v[130:133], v[200:203], v[34:49]
	v_mfma_f32_32x32x16_bf16 v[18:33], v[134:137], v[66:69], v[18:33]
	ds_read_b64_tr_b16 v[66:67], v180 offset:0x600
	ds_read_b64_tr_b16 v[68:69], v180 offset:0xe00
	v_exp_f32_e32 v197, v74
	v_exp_f32_e32 v199, v75
	v_exp_f32_e32 v201, v76
	v_exp_f32_e32 v203, v77
	v_exp_f32_e32 v196, v90
	v_mfma_f32_32x32x16_bf16 v[18:33], v[138:141], v[70:73], v[18:33]
	ds_read_b64_tr_b16 v[70:71], v180 offset:0x1600
	ds_read_b64_tr_b16 v[72:73], v180 offset:0x1e00
	ds_read_b64_tr_b16 v[74:75], v180 offset:0x2600
	ds_read_b64_tr_b16 v[76:77], v180 offset:0x2e00
	v_exp_f32_e32 v198, v91
	v_exp_f32_e32 v200, v92
	v_exp_f32_e32 v202, v93
	v_mfma_f32_32x32x16_bf16 v[18:33], v[126:129], v[82:85], v[18:33]
	ds_read_b64_tr_b16 v[82:83], v180 offset:0x3600
	ds_read_b64_tr_b16 v[84:85], v180 offset:0x3e00
	s_waitcnt lgkmcnt(0)
	v_mfma_f32_32x32x16_bf16 v[18:33], v[130:133], v[86:89], v[18:33]
	v_mfma_f32_32x32x16_bf16 v[2:17], v[134:137], v[66:69], v[2:17]
	s_barrier
	s_waitcnt vmcnt(0)
	v_exp_f32_e32 v222, v94
	v_exp_f32_e32 v223, v78
	v_exp_f32_e32 v224, v95
	v_mfma_f32_32x32x16_bf16 v[2:17], v[138:141], v[70:73], v[2:17]
	v_exp_f32_e32 v226, v79
	v_exp_f32_e32 v227, v96
	v_exp_f32_e32 v228, v80
	v_exp_f32_e32 v229, v97
	v_exp_f32_e32 v230, v81
	s_waitcnt vmcnt(3)
	ds_write_b128 v183, v[142:145]
	s_waitcnt vmcnt(1)
	ds_write_b128 v184, v[154:157]
	ds_write_b128 v181, v[146:149] offset:32768
	s_waitcnt vmcnt(0)
	ds_write_b128 v182, v[150:153] offset:32768
	s_waitcnt lgkmcnt(0)
	v_mfma_f32_32x32x16_bf16 v[2:17], v[126:129], v[74:77], v[2:17]
	s_barrier
	v_mfma_f32_32x32x16_bf16 v[2:17], v[130:133], v[82:85], v[2:17]
	s_cmp_eq_u32 s82, s99
	s_cbranch_scc1 .Lattn_refill_b
.Lattn_back_b:
	ds_read_b128 v[126:129], v186 offset:32768
	ds_read_b128 v[130:133], v186 offset:40960
	ds_read_b128 v[134:137], v187 offset:32768
	ds_read_b128 v[138:141], v187 offset:40960
	v_add_f32_e32 v98, 0, v212
	v_add_f32_e32 v98, v214, v98
	v_add_f32_e32 v98, v216, v98
	v_add_f32_e32 v98, v218, v98
	v_add_f32_e32 v98, v204, v98
	v_add_f32_e32 v98, v206, v98
	v_add_f32_e32 v98, v208, v98
	s_waitcnt lgkmcnt(3)
	v_mfma_f32_32x32x16_bf16 v[82:97], v[126:129], v[118:121], v[236:251]
	v_add_f32_e32 v98, v210, v98
	v_add_f32_e32 v98, v196, v98
	v_add_f32_e32 v98, v198, v98
	v_add_f32_e32 v98, v200, v98
	v_add_f32_e32 v98, v202, v98
	v_add_f32_e32 v98, v222, v98
	v_add_f32_e32 v98, v224, v98
	s_waitcnt lgkmcnt(2)
	v_mfma_f32_32x32x16_bf16 v[66:81], v[130:133], v[118:121], v[236:251]
	v_add_f32_e32 v98, v227, v98
	ds_read_b128 v[126:129], v188 offset:32768
	ds_read_b128 v[142:145], v188 offset:40960
	ds_read_b128 v[146:149], v189 offset:32768
	ds_read_b128 v[154:157], v189 offset:40960
	v_add_f32_e32 v98, v229, v98
	v_add_f32_e32 v98, v213, v98
	v_add_f32_e32 v98, v215, v98
	v_add_f32_e32 v98, v217, v98
	v_add_f32_e32 v98, v221, v98
	s_waitcnt lgkmcnt(5)
	v_mfma_f32_32x32x16_bf16 v[82:97], v[134:137], v[114:117], v[82:97]
	v_add_f32_e32 v98, v205, v98
	v_add_f32_e32 v98, v207, v98
	v_add_f32_e32 v98, v209, v98
	v_add_f32_e32 v98, v211, v98
	v_add_f32_e32 v98, v197, v98
	v_add_f32_e32 v98, v199, v98
	v_add_f32_e32 v98, v201, v98
	s_waitcnt lgkmcnt(4)
	v_mfma_f32_32x32x16_bf16 v[66:81], v[138:141], v[114:117], v[66:81]
	v_add_f32_e32 v98, v203, v98
	v_add_f32_e32 v98, v223, v98
	v_add_f32_e32 v98, v226, v98
	v_add_f32_e32 v98, v228, v98
	v_add_f32_e32 v98, v230, v98
	s_waitcnt lgkmcnt(3)
	v_mfma_f32_32x32x16_bf16 v[82:97], v[126:129], v[110:113], v[82:97]
	v_cvt_pk_bf16_f32 v150, v212, v214
	v_cvt_pk_bf16_f32 v151, v216, v218
	v_cvt_pk_bf16_f32 v152, v204, v206
	v_cvt_pk_bf16_f32 v153, v208, v210
	v_cvt_pk_bf16_f32 v134, v196, v198
	v_cvt_pk_bf16_f32 v135, v200, v202
	v_cvt_pk_bf16_f32 v136, v222, v224
	s_waitcnt lgkmcnt(2)
	v_mfma_f32_32x32x16_bf16 v[66:81], v[142:145], v[110:113], v[66:81]
	v_cvt_pk_bf16_f32 v137, v227, v229
	v_cvt_pk_bf16_f32 v130, v213, v215
	v_cvt_pk_bf16_f32 v131, v217, v221
	v_cvt_pk_bf16_f32 v132, v205, v207
	v_cvt_pk_bf16_f32 v133, v209, v211
	v_cvt_pk_bf16_f32 v126, v197, v199
	v_cvt_pk_bf16_f32 v127, v201, v203
	s_waitcnt lgkmcnt(1)
	v_mfma_f32_32x32x16_bf16 v[82:97], v[146:149], v[106:109], v[82:97]
	v_cvt_pk_bf16_f32 v128, v223, v226
	v_cvt_pk_bf16_f32 v129, v228, v230
	s_waitcnt lgkmcnt(0)
	v_mfma_f32_32x32x16_bf16 v[66:81], v[154:157], v[106:109], v[66:81]
	v_add_co_u32_e32 v142, vcc, 0xa0000, v160
	s_nop 1
	v_addc_co_u32_e32 v143, vcc, 0, v161, vcc
	v_add_co_u32_e32 v146, vcc, 0xf0000, v160
	s_nop 1
	v_addc_co_u32_e32 v147, vcc, 0, v161, vcc
	global_load_dwordx4 v[138:141], v[142:143], off offset:2048
	s_nop 0
	global_load_dwordx4 v[142:145], v[142:143], off
	s_nop 0
	global_load_dwordx4 v[154:157], v[146:147], off offset:2048
	s_nop 0
	global_load_dwordx4 v[146:149], v[146:147], off
	s_and_saveexec_b64 s[2:3], s[8:9]
	s_cbranch_execz .LBB0_345
	ds_read2_b32 v[196:197], v194 offset0:64 offset1:65
	ds_read2_b32 v[198:199], v194 offset0:80 offset1:81
	ds_read2_b32 v[200:201], v194 offset0:82 offset1:83
	ds_read2_b32 v[202:203], v194 offset0:88 offset1:89
	ds_read2_b32 v[204:205], v194 offset0:90 offset1:91
	ds_read2_b32 v[206:207], v194 offset0:66 offset1:67
	ds_read2_b32 v[208:209], v194 offset0:72 offset1:73
	ds_read2_b32 v[210:211], v194 offset0:74 offset1:75
	s_waitcnt lgkmcnt(7)
	v_pk_add_f32 v[82:83], v[82:83], v[196:197]
	s_waitcnt lgkmcnt(3)
	v_pk_add_f32 v[96:97], v[96:97], v[204:205]
	v_pk_add_f32 v[94:95], v[94:95], v[202:203]
	v_pk_add_f32 v[92:93], v[92:93], v[200:201]
	v_pk_add_f32 v[90:91], v[90:91], v[198:199]
	s_waitcnt lgkmcnt(0)
	v_pk_add_f32 v[88:89], v[88:89], v[210:211]
	v_pk_add_f32 v[86:87], v[86:87], v[208:209]
	v_pk_add_f32 v[84:85], v[84:85], v[206:207]
	ds_read2_b32 v[196:197], v194 offset0:112 offset1:113
	ds_read2_b32 v[198:199], v194 offset0:114 offset1:115
	ds_read2_b32 v[200:201], v194 offset0:120 offset1:121
	ds_read2_b32 v[202:203], v194 offset0:122 offset1:123
	ds_read2_b32 v[204:205], v194 offset0:96 offset1:97
	ds_read2_b32 v[206:207], v194 offset0:98 offset1:99
	ds_read2_b32 v[208:209], v194 offset0:104 offset1:105
	ds_read2_b32 v[210:211], v194 offset0:106 offset1:107
	s_waitcnt lgkmcnt(4)
	v_pk_add_f32 v[80:81], v[80:81], v[202:203]
	v_pk_add_f32 v[78:79], v[78:79], v[200:201]
	v_pk_add_f32 v[76:77], v[76:77], v[198:199]
	v_pk_add_f32 v[74:75], v[74:75], v[196:197]
	s_waitcnt lgkmcnt(0)
	v_pk_add_f32 v[72:73], v[72:73], v[210:211]
	v_pk_add_f32 v[70:71], v[70:71], v[208:209]
	v_pk_add_f32 v[68:69], v[68:69], v[206:207]
	v_pk_add_f32 v[66:67], v[66:67], v[204:205]
	s_branch .LBB0_345
.LBB0_350:
	v_mov_b32_e32 v234, v176
	s_nop 1
	v_permlane32_swap_b32_e32 v176, v234
	v_add_f32_e32 v176, v176, v234
	s_cmp_eq_u32 s79, s99
	s_cbranch_scc1 .Lattn_refill_t
.Lattn_back_t:
	v_add_f32_e32 v98, 0, v199
	ds_read_b128 v[122:125], v186 offset:49152
	ds_read_b128 v[126:129], v186 offset:57344
	ds_read_b128 v[130:133], v187 offset:49152
	ds_read_b128 v[134:137], v187 offset:57344
	ds_read_b128 v[138:141], v188 offset:49152
	ds_read_b128 v[142:145], v188 offset:57344
	v_add_f32_e32 v98, v201, v98
	v_add_f32_e32 v98, v202, v98
	v_add_f32_e32 v98, v205, v98
	v_add_f32_e32 v98, v207, v98
	v_add_f32_e32 v98, v209, v98
	s_waitcnt lgkmcnt(5)
	v_mfma_f32_32x32x16_bf16 v[82:97], v[122:125], v[118:121], v[236:251]
	v_add_f32_e32 v98, v211, v98
	v_add_f32_e32 v98, v213, v98
	v_add_f32_e32 v98, v215, v98
	v_add_f32_e32 v98, v216, v98
	v_add_f32_e32 v98, v217, v98
	v_add_f32_e32 v98, v218, v98
	v_add_f32_e32 v98, v221, v98
	s_waitcnt lgkmcnt(4)
	v_mfma_f32_32x32x16_bf16 v[66:81], v[126:129], v[118:121], v[236:251]
	v_add_f32_e32 v98, v222, v98
	v_add_f32_e32 v98, v223, v98
	v_add_f32_e32 v98, v224, v98
	v_add_f32_e32 v98, v195, v98
	v_add_f32_e32 v98, v196, v98
	v_add_f32_e32 v98, v197, v98
	v_add_f32_e32 v98, v198, v98
	s_waitcnt lgkmcnt(3)
	v_mfma_f32_32x32x16_bf16 v[82:97], v[130:133], v[114:117], v[82:97]
	v_add_f32_e32 v98, v200, v98
	ds_read_b128 v[146:149], v189 offset:49152
	ds_read_b128 v[154:157], v189 offset:57344
	v_add_f32_e32 v98, v203, v98
	v_add_f32_e32 v98, v204, v98
	v_add_f32_e32 v98, v206, v98
	v_add_f32_e32 v98, v208, v98
	v_add_f32_e32 v98, v210, v98
	s_waitcnt lgkmcnt(4)
	v_mfma_f32_32x32x16_bf16 v[66:81], v[134:137], v[114:117], v[66:81]
	v_add_f32_e32 v98, v212, v98
	v_add_f32_e32 v98, v214, v98
	v_add_f32_e32 v98, v150, v98
	v_add_f32_e32 v98, v151, v98
	v_add_f32_e32 v98, v152, v98
	v_add_f32_e32 v100, v153, v98
	v_mov_b32_e32 v122, v100
	s_waitcnt lgkmcnt(3)
	v_mfma_f32_32x32x16_bf16 v[82:97], v[138:141], v[110:113], v[82:97]
	v_permlane32_swap_b32_e32 v100, v122
	v_cvt_pk_bf16_f32 v114, v199, v201
	v_cvt_pk_bf16_f32 v115, v202, v205
	v_cvt_pk_bf16_f32 v116, v207, v209
	v_cvt_pk_bf16_f32 v117, v211, v213
	s_waitcnt lgkmcnt(2)
	v_mfma_f32_32x32x16_bf16 v[66:81], v[142:145], v[110:113], v[66:81]
	v_cvt_pk_bf16_f32 v110, v215, v216
	v_cvt_pk_bf16_f32 v111, v217, v218
	v_cvt_pk_bf16_f32 v112, v221, v222
	v_cvt_pk_bf16_f32 v113, v223, v224
	v_cvt_pk_bf16_f32 v118, v195, v196
	v_cvt_pk_bf16_f32 v119, v197, v198
	v_cvt_pk_bf16_f32 v120, v200, v203
	s_waitcnt lgkmcnt(1)
	v_mfma_f32_32x32x16_bf16 v[82:97], v[146:149], v[106:109], v[82:97]
	v_cvt_pk_bf16_f32 v121, v204, v206
	s_waitcnt lgkmcnt(0)
	v_mfma_f32_32x32x16_bf16 v[66:81], v[154:157], v[106:109], v[66:81]
	v_cvt_pk_bf16_f32 v106, v208, v210
	v_cvt_pk_bf16_f32 v107, v212, v214
	v_cvt_pk_bf16_f32 v108, v150, v151
	v_cvt_pk_bf16_f32 v109, v152, v153
	s_and_saveexec_b64 s[2:3], s[8:9]
	s_cbranch_execz .LBB0_352
	v_sub_u32_e32 v98, s79, v178
	v_lshlrev_b32_e32 v98, 2, v98
	v_lshlrev_b32_e32 v101, 2, v179
	v_add3_u32 v98, s1, v98, v101
	ds_read2_b32 v[124:125], v98 offset0:240 offset1:241
	ds_read2_b32 v[126:127], v98 offset0:242 offset1:243
	ds_read2_b32 v[128:129], v98 offset0:248 offset1:249
	ds_read2_b32 v[130:131], v98 offset0:250 offset1:251
	ds_read2_b32 v[132:133], v98 offset0:224 offset1:225
	ds_read2_b32 v[134:135], v98 offset0:226 offset1:227
	ds_read2_b32 v[136:137], v98 offset0:232 offset1:233
	ds_read2_b32 v[138:139], v98 offset0:234 offset1:235
	s_waitcnt lgkmcnt(4)
	v_pk_add_f32 v[96:97], v[96:97], v[130:131]
	v_pk_add_f32 v[94:95], v[94:95], v[128:129]
	v_pk_add_f32 v[92:93], v[92:93], v[126:127]
	v_pk_add_f32 v[90:91], v[90:91], v[124:125]
	s_waitcnt lgkmcnt(0)
	v_pk_add_f32 v[88:89], v[88:89], v[138:139]
	v_pk_add_f32 v[86:87], v[86:87], v[136:137]
	v_pk_add_f32 v[84:85], v[84:85], v[134:135]
	v_pk_add_f32 v[82:83], v[82:83], v[132:133]
	v_add_u32_e32 v136, 0x420, v98
	v_add_u32_e32 v138, 0x428, v98
	v_add_u32_e32 v124, 0x440, v98
	v_add_u32_e32 v126, 0x448, v98
	v_add_u32_e32 v128, 0x460, v98
	v_add_u32_e32 v101, 0x400, v98
	v_add_u32_e32 v123, 0x408, v98
	v_add_u32_e32 v98, 0x468, v98
	ds_read2_b32 v[124:125], v124 offset1:1
	ds_read2_b32 v[126:127], v126 offset1:1
	ds_read2_b32 v[128:129], v128 offset1:1
	ds_read2_b32 v[130:131], v98 offset1:1
	ds_read2_b32 v[132:133], v101 offset1:1
	ds_read2_b32 v[134:135], v123 offset1:1
	ds_read2_b32 v[136:137], v136 offset1:1
	ds_read2_b32 v[138:139], v138 offset1:1
	s_waitcnt lgkmcnt(4)
	v_pk_add_f32 v[80:81], v[80:81], v[130:131]
	v_pk_add_f32 v[78:79], v[78:79], v[128:129]
	v_pk_add_f32 v[76:77], v[76:77], v[126:127]
	v_pk_add_f32 v[74:75], v[74:75], v[124:125]
	s_waitcnt lgkmcnt(0)
	v_pk_add_f32 v[72:73], v[72:73], v[138:139]
	v_pk_add_f32 v[70:71], v[70:71], v[136:137]
	v_pk_add_f32 v[68:69], v[68:69], v[134:135]
	v_pk_add_f32 v[66:67], v[66:67], v[132:133]

.Lattn_refill_a:
	s_sub_i32 s101, s100, s98
	v_mov_b32_e32 v234, v191
	s_mov_b64 s[8:9], 0
	s_add_i32 s99, s98, 0xffffff41
	s_ashr_i32 s99, s99, 6
	s_add_i32 s99, s99, 1
	s_lshl_b32 s99, s99, 6
	s_cmp_gt_i32 s101, 0xffffff41
	s_cbranch_scc0 .Lattn_fill_a
	v_mov_b32_e32 v234, v190
	s_mov_b64 s[8:9], -1
	s_add_i32 s99, s98, 0x9e
	s_ashr_i32 s99, s99, 6
	s_add_i32 s99, s99, 1
	s_lshl_b32 s99, s99, 6
	s_cmp_gt_i32 s101, 0x9e
	s_cbranch_scc0 .Lattn_fill_a
	v_mov_b32_e32 v234, v192
	s_mov_b64 s[8:9], 0
	s_mov_b32 s99, 0x7fffffff
.Lattn_fill_a:
	v_mov_b32_e32 v236, v234
	v_mov_b32_e32 v237, v234
	v_mov_b32_e32 v238, v234
	v_mov_b32_e32 v239, v234
	v_mov_b32_e32 v240, v234
	v_mov_b32_e32 v241, v234
	v_mov_b32_e32 v242, v234
	v_mov_b32_e32 v243, v234
	v_mov_b32_e32 v244, v234
	v_mov_b32_e32 v245, v234
	v_mov_b32_e32 v246, v234
	v_mov_b32_e32 v247, v234
	v_mov_b32_e32 v248, v234
	v_mov_b32_e32 v249, v234
	v_mov_b32_e32 v250, v234
	v_mov_b32_e32 v251, v234
	s_nop 1
	s_branch .Lattn_back_a
.Lattn_refill_b:
	s_mov_b32 s100, s82
	s_sub_i32 s101, s100, s98
	v_mov_b32_e32 v234, v191
	s_mov_b64 s[8:9], 0
	s_add_i32 s99, s98, 0xffffff41
	s_ashr_i32 s99, s99, 6
	s_add_i32 s99, s99, 1
	s_lshl_b32 s99, s99, 6
	s_cmp_gt_i32 s101, 0xffffff41
	s_cbranch_scc0 .Lattn_fill_b
	v_mov_b32_e32 v234, v190
	s_mov_b64 s[8:9], -1
	s_add_i32 s99, s98, 0x9e
	s_ashr_i32 s99, s99, 6
	s_add_i32 s99, s99, 1
	s_lshl_b32 s99, s99, 6
	s_cmp_gt_i32 s101, 0x9e
	s_cbranch_scc0 .Lattn_fill_b
	v_mov_b32_e32 v234, v192
	s_mov_b64 s[8:9], 0
	s_mov_b32 s99, 0x7fffffff

.Lattn_refill_t:
	s_mov_b32 s100, s79
	s_sub_i32 s101, s100, s98
	v_mov_b32_e32 v234, v191
	s_mov_b64 s[8:9], 0
	s_add_i32 s99, s98, 0xffffff41
	s_ashr_i32 s99, s99, 6
	s_add_i32 s99, s99, 1
	s_lshl_b32 s99, s99, 6
	s_cmp_gt_i32 s101, 0xffffff41
	s_cbranch_scc0 .Lattn_fill_t
	v_mov_b32_e32 v234, v190
	s_mov_b64 s[8:9], -1
	s_add_i32 s99, s98, 0x9e
	s_ashr_i32 s99, s99, 6
	s_add_i32 s99, s99, 1
	s_lshl_b32 s99, s99, 6
	s_cmp_gt_i32 s101, 0x9e
	s_cbranch_scc0 .Lattn_fill_t
	v_mov_b32_e32 v234, v192
	s_mov_b64 s[8:9], 0
	s_mov_b32 s99, 0x7fffffff

.LBB0_767:
	s_ashr_i32 s18, s21, 3
	s_add_i32 s18, s23, s18
	s_lshr_b32 s21, s18, 5
	s_and_b32 s18, s18, 31
	s_lshl_b32 s21, s21, 2
	s_and_b32 s19, s18, 3
	s_add_i32 s58, s21, s19
	s_lshr_b32 s86, s18, 2

.LBB0_779:
	s_ashr_i32 s20, s22, 3
	s_add_i32 s20, s28, s20
	s_ashr_i32 s21, s20, 31
	s_lshr_b32 s21, s21, 27
	s_add_i32 s21, s20, s21
	s_ashr_i32 s22, s21, 5
	s_lshl_b32 s22, s22, 2
	s_sub_i32 s23, 0x80, s22
	s_min_i32 s23, s23, 4
	s_abs_i32 s28, s23
	v_cvt_f32_u32_e32 v0, s28
	s_sub_i32 s40, 0, s28
	s_andn2_b32 s21, s21, 31
	s_sub_i32 s20, s20, s21
	v_rcp_iflag_f32_e32 v0, v0
	s_abs_i32 s21, s20
	s_xor_b32 s29, s20, s23
	s_ashr_i32 s29, s29, 31
	v_mul_f32_e32 v0, 0x4f7ffffe, v0
	v_cvt_u32_f32_e32 v0, v0
	s_nop 0
	v_readfirstlane_b32 s41, v0
	s_mul_i32 s40, s40, s41
	s_mul_hi_u32 s40, s41, s40
	s_add_i32 s41, s41, s40
	s_mul_hi_u32 s40, s21, s41
	s_mul_i32 s41, s40, s28
	s_sub_i32 s21, s21, s41
	s_add_i32 s51, s40, 1
	s_sub_i32 s41, s21, s28
	s_cmp_ge_u32 s21, s28
	s_cselect_b32 s40, s51, s40
	s_cselect_b32 s21, s41, s21
	s_add_i32 s41, s40, 1
	s_cmp_ge_u32 s21, s28
	s_cselect_b32 s21, s41, s40
	s_xor_b32 s21, s21, s29
	s_sub_i32 s51, s21, s29
	s_mul_i32 s21, s51, s23
	s_sub_i32 s20, s20, s21
	s_add_i32 s52, s22, s20

.LBB0_871:
	s_cmp_gt_i32 s94, 10
	s_cselect_b64 s[0:1], -1, 0
	s_xor_b64 s[2:3], s[2:3], -1
	s_or_b64 s[0:1], s[0:1], s[2:3]
	s_and_b64 vcc, exec, s[0:1]
	s_cbranch_vccnz .LBB0_875
	s_load_dword s0, s[42:43], 0x0
	v_and_b32_e32 v1, 63, v150
	v_lshrrev_b32_e32 v2, 6, v150
	v_mov_b32_e32 v14, 0x358637bd
	s_mov_b32 s22, 0x800000
	v_readfirstlane_b32 s1, v151
	v_readfirstlane_b32 s11, v2
	s_waitcnt lgkmcnt(0)
	s_lshl_b32 s2, s1, 3
	s_add_u32 s10, s2, s11
	s_lshl_b32 s23, s0, 3
	s_lshl_b32 s12, s23, 12
	s_mov_b32 s13, 0
	s_lshl_b32 s18, s23, 2
	s_mov_b32 s19, 0
	s_lshl_b32 s20, s23, 13
	s_mov_b32 s21, 0
	v_lshlrev_b32_e32 v10, 5, v1
	v_mov_b32_e32 v11, 0
	v_lshl_add_u64 v[10:11], s[88:89], 0, v[10:11]
	s_mov_b64 s[14:15], 0x1000
	v_lshl_add_u64 v[12:13], v[10:11], 0, s[14:15]
	global_load_dwordx4 v[16:19], v[10:11], off
	global_load_dwordx4 v[20:23], v[10:11], off offset:16
	global_load_dwordx4 v[24:27], v[10:11], off offset:2048
	global_load_dwordx4 v[28:31], v[10:11], off offset:2064
	global_load_dwordx4 v[32:35], v[12:13], off
	global_load_dwordx4 v[36:39], v[12:13], off offset:16
	global_load_dwordx4 v[40:43], v[12:13], off offset:2048
	global_load_dwordx4 v[44:47], v[12:13], off offset:2064
	s_lshl_b32 s14, s10, 12
	v_lshlrev_b32_e32 v4, 4, v1
	v_add_u32_e32 v4, s14, v4
	v_mov_b32_e32 v5, 0
	s_add_u32 s16, s92, 0x6400000
	s_addc_u32 s17, s93, 0
	v_lshl_add_u64 v[4:5], s[16:17], 0, v[4:5]
	s_lshl_b32 s14, s10, 2
	v_mov_b32_e32 v6, s14
	v_mov_b32_e32 v7, 0
	s_add_u32 s16, s92, 0x5f80000
	s_addc_u32 s17, s93, 0
	v_lshl_add_u64 v[6:7], s[16:17], 0, v[6:7]
	s_lshl_b32 s14, s10, 13
	s_add_u32 s14, s14, 0x1000
	v_lshlrev_b32_e32 v8, 5, v1
	v_add_u32_e32 v8, s14, v8
	v_mov_b32_e32 v9, 0
	v_lshl_add_u64 v[8:9], s[90:91], 0, v[8:9]
	global_load_dword v144, v[6:7], off
	global_load_dwordx4 v[80:83], v[4:5], off
	global_load_dwordx4 v[84:87], v[4:5], off offset:1024
	global_load_dwordx4 v[88:91], v[4:5], off offset:2048
	global_load_dwordx4 v[92:95], v[4:5], off offset:3072
	v_lshl_add_u64 v[4:5], v[4:5], 0, s[12:13]
	v_lshl_add_u64 v[6:7], v[6:7], 0, s[18:19]
	global_load_dword v145, v[6:7], off
	global_load_dwordx4 v[96:99], v[4:5], off
	global_load_dwordx4 v[100:103], v[4:5], off offset:1024
	global_load_dwordx4 v[104:107], v[4:5], off offset:2048
	global_load_dwordx4 v[108:111], v[4:5], off offset:3072
	v_lshl_add_u64 v[4:5], v[4:5], 0, s[12:13]
	v_lshl_add_u64 v[6:7], v[6:7], 0, s[18:19]
	global_load_dword v146, v[6:7], off
	global_load_dwordx4 v[112:115], v[4:5], off
	global_load_dwordx4 v[116:119], v[4:5], off offset:1024
	global_load_dwordx4 v[120:123], v[4:5], off offset:2048
	global_load_dwordx4 v[124:127], v[4:5], off offset:3072
	v_lshl_add_u64 v[4:5], v[4:5], 0, s[12:13]
	v_lshl_add_u64 v[6:7], v[6:7], 0, s[18:19]
	global_load_dword v147, v[6:7], off
	global_load_dwordx4 v[128:131], v[4:5], off
	global_load_dwordx4 v[132:135], v[4:5], off offset:1024
	global_load_dwordx4 v[136:139], v[4:5], off offset:2048
	global_load_dwordx4 v[140:143], v[4:5], off offset:3072
	v_lshl_add_u64 v[4:5], v[4:5], 0, s[12:13]
	v_lshl_add_u64 v[6:7], v[6:7], 0, s[18:19]
	s_waitcnt vmcnt(0)
.Lfin_loop:
	s_cmp_lt_u32 s10, 0x10000
	s_cbranch_scc0 .Lfin_done
	s_waitcnt vmcnt(39)
	v_fmamk_f32 v2, v144, 0x3a000000, v14
	v_mul_f32_e32 v15, 0x4b800000, v2
	v_cmp_gt_f32_e32 vcc, s22, v2
	s_nop 1
	v_cndmask_b32_e32 v2, v2, v15, vcc
	v_rsq_f32_e32 v2, v2
	s_nop 0
	v_mul_f32_e32 v15, 0x45800000, v2
	v_cndmask_b32_e32 v2, v2, v15, vcc
	v_lshlrev_b32_e32 v48, 16, v80
	v_and_b32_e32 v49, 0xffff0000, v80
	v_lshlrev_b32_e32 v50, 16, v81
	v_and_b32_e32 v51, 0xffff0000, v81
	v_lshlrev_b32_e32 v52, 16, v82
	v_and_b32_e32 v53, 0xffff0000, v82
	v_lshlrev_b32_e32 v54, 16, v83
	v_and_b32_e32 v55, 0xffff0000, v83
	v_pk_mul_f32 v[48:49], v[2:3], v[48:49] op_sel_hi:[0,1]
	v_pk_mul_f32 v[50:51], v[2:3], v[50:51] op_sel_hi:[0,1]
	v_pk_mul_f32 v[52:53], v[2:3], v[52:53] op_sel_hi:[0,1]
	v_pk_mul_f32 v[54:55], v[2:3], v[54:55] op_sel_hi:[0,1]
	v_pk_mul_f32 v[48:49], v[16:17], v[48:49]
	v_pk_mul_f32 v[50:51], v[18:19], v[50:51]
	v_pk_mul_f32 v[52:53], v[20:21], v[52:53]
	v_pk_mul_f32 v[54:55], v[22:23], v[54:55]
	global_store_dwordx4 v[8:9], v[48:51], off offset:-4096
	global_store_dwordx4 v[8:9], v[52:55], off offset:-4080
	v_lshlrev_b32_e32 v56, 16, v84
	v_and_b32_e32 v57, 0xffff0000, v84
	v_lshlrev_b32_e32 v58, 16, v85
	v_and_b32_e32 v59, 0xffff0000, v85
	v_lshlrev_b32_e32 v60, 16, v86
	v_and_b32_e32 v61, 0xffff0000, v86
	v_lshlrev_b32_e32 v62, 16, v87
	v_and_b32_e32 v63, 0xffff0000, v87
	v_pk_mul_f32 v[56:57], v[2:3], v[56:57] op_sel_hi:[0,1]
	v_pk_mul_f32 v[58:59], v[2:3], v[58:59] op_sel_hi:[0,1]
	v_pk_mul_f32 v[60:61], v[2:3], v[60:61] op_sel_hi:[0,1]
	v_pk_mul_f32 v[62:63], v[2:3], v[62:63] op_sel_hi:[0,1]
	v_pk_mul_f32 v[56:57], v[24:25], v[56:57]
	v_pk_mul_f32 v[58:59], v[26:27], v[58:59]
	v_pk_mul_f32 v[60:61], v[28:29], v[60:61]
	v_pk_mul_f32 v[62:63], v[30:31], v[62:63]
	global_store_dwordx4 v[8:9], v[56:59], off offset:-2048
	global_store_dwordx4 v[8:9], v[60:63], off offset:-2032
	v_lshlrev_b32_e32 v64, 16, v88
	v_and_b32_e32 v65, 0xffff0000, v88
	v_lshlrev_b32_e32 v66, 16, v89
	v_and_b32_e32 v67, 0xffff0000, v89
	v_lshlrev_b32_e32 v68, 16, v90
	v_and_b32_e32 v69, 0xffff0000, v90
	v_lshlrev_b32_e32 v70, 16, v91
	v_and_b32_e32 v71, 0xffff0000, v91
	v_pk_mul_f32 v[64:65], v[2:3], v[64:65] op_sel_hi:[0,1]
	v_pk_mul_f32 v[66:67], v[2:3], v[66:67] op_sel_hi:[0,1]
	v_pk_mul_f32 v[68:69], v[2:3], v[68:69] op_sel_hi:[0,1]
	v_pk_mul_f32 v[70:71], v[2:3], v[70:71] op_sel_hi:[0,1]
	v_pk_mul_f32 v[64:65], v[32:33], v[64:65]
	v_pk_mul_f32 v[66:67], v[34:35], v[66:67]
	v_pk_mul_f32 v[68:69], v[36:37], v[68:69]
	v_pk_mul_f32 v[70:71], v[38:39], v[70:71]
	global_store_dwordx4 v[8:9], v[64:67], off offset:0
	global_store_dwordx4 v[8:9], v[68:71], off offset:16
	v_lshlrev_b32_e32 v72, 16, v92
	v_and_b32_e32 v73, 0xffff0000, v92
	v_lshlrev_b32_e32 v74, 16, v93
	v_and_b32_e32 v75, 0xffff0000, v93
	v_lshlrev_b32_e32 v76, 16, v94
	v_and_b32_e32 v77, 0xffff0000, v94
	v_lshlrev_b32_e32 v78, 16, v95
	v_and_b32_e32 v79, 0xffff0000, v95
	v_pk_mul_f32 v[72:73], v[2:3], v[72:73] op_sel_hi:[0,1]
	v_pk_mul_f32 v[74:75], v[2:3], v[74:75] op_sel_hi:[0,1]
	v_pk_mul_f32 v[76:77], v[2:3], v[76:77] op_sel_hi:[0,1]
	v_pk_mul_f32 v[78:79], v[2:3], v[78:79] op_sel_hi:[0,1]
	v_pk_mul_f32 v[72:73], v[40:41], v[72:73]
	v_pk_mul_f32 v[74:75], v[42:43], v[74:75]
	v_pk_mul_f32 v[76:77], v[44:45], v[76:77]
	v_pk_mul_f32 v[78:79], v[46:47], v[78:79]
	global_store_dwordx4 v[8:9], v[72:75], off offset:2048
	global_store_dwordx4 v[8:9], v[76:79], off offset:2064
	v_lshl_add_u64 v[8:9], v[8:9], 0, s[20:21]
	s_add_u32 s10, s10, s23
	global_load_dword v144, v[6:7], off
	global_load_dwordx4 v[80:83], v[4:5], off
	global_load_dwordx4 v[84:87], v[4:5], off offset:1024
	global_load_dwordx4 v[88:91], v[4:5], off offset:2048
	global_load_dwordx4 v[92:95], v[4:5], off offset:3072
	v_lshl_add_u64 v[4:5], v[4:5], 0, s[12:13]
	v_lshl_add_u64 v[6:7], v[6:7], 0, s[18:19]
	s_cmp_lt_u32 s10, 0x10000
	s_cbranch_scc0 .Lfin_done
	s_waitcnt vmcnt(39)
	v_fmamk_f32 v2, v145, 0x3a000000, v14
	v_mul_f32_e32 v15, 0x4b800000, v2
	v_cmp_gt_f32_e32 vcc, s22, v2
	s_nop 1
	v_cndmask_b32_e32 v2, v2, v15, vcc
	v_rsq_f32_e32 v2, v2
	s_nop 0
	v_mul_f32_e32 v15, 0x45800000, v2
	v_cndmask_b32_e32 v2, v2, v15, vcc
	v_lshlrev_b32_e32 v48, 16, v96
	v_and_b32_e32 v49, 0xffff0000, v96
	v_lshlrev_b32_e32 v50, 16, v97
	v_and_b32_e32 v51, 0xffff0000, v97
	v_lshlrev_b32_e32 v52, 16, v98
	v_and_b32_e32 v53, 0xffff0000, v98
	v_lshlrev_b32_e32 v54, 16, v99
	v_and_b32_e32 v55, 0xffff0000, v99
	v_pk_mul_f32 v[48:49], v[2:3], v[48:49] op_sel_hi:[0,1]
	v_pk_mul_f32 v[50:51], v[2:3], v[50:51] op_sel_hi:[0,1]
	v_pk_mul_f32 v[52:53], v[2:3], v[52:53] op_sel_hi:[0,1]
	v_pk_mul_f32 v[54:55], v[2:3], v[54:55] op_sel_hi:[0,1]
	v_pk_mul_f32 v[48:49], v[16:17], v[48:49]
	v_pk_mul_f32 v[50:51], v[18:19], v[50:51]
	v_pk_mul_f32 v[52:53], v[20:21], v[52:53]
	v_pk_mul_f32 v[54:55], v[22:23], v[54:55]
	global_store_dwordx4 v[8:9], v[48:51], off offset:-4096
	global_store_dwordx4 v[8:9], v[52:55], off offset:-4080
	v_lshlrev_b32_e32 v56, 16, v100
	v_and_b32_e32 v57, 0xffff0000, v100
	v_lshlrev_b32_e32 v58, 16, v101
	v_and_b32_e32 v59, 0xffff0000, v101
	v_lshlrev_b32_e32 v60, 16, v102
	v_and_b32_e32 v61, 0xffff0000, v102
	v_lshlrev_b32_e32 v62, 16, v103
	v_and_b32_e32 v63, 0xffff0000, v103
	v_pk_mul_f32 v[56:57], v[2:3], v[56:57] op_sel_hi:[0,1]
	v_pk_mul_f32 v[58:59], v[2:3], v[58:59] op_sel_hi:[0,1]
	v_pk_mul_f32 v[60:61], v[2:3], v[60:61] op_sel_hi:[0,1]
	v_pk_mul_f32 v[62:63], v[2:3], v[62:63] op_sel_hi:[0,1]
	v_pk_mul_f32 v[56:57], v[24:25], v[56:57]
	v_pk_mul_f32 v[58:59], v[26:27], v[58:59]
	v_pk_mul_f32 v[60:61], v[28:29], v[60:61]
	v_pk_mul_f32 v[62:63], v[30:31], v[62:63]
	global_store_dwordx4 v[8:9], v[56:59], off offset:-2048
	global_store_dwordx4 v[8:9], v[60:63], off offset:-2032
	v_lshlrev_b32_e32 v64, 16, v104
	v_and_b32_e32 v65, 0xffff0000, v104
	v_lshlrev_b32_e32 v66, 16, v105
	v_and_b32_e32 v67, 0xffff0000, v105
	v_lshlrev_b32_e32 v68, 16, v106
	v_and_b32_e32 v69, 0xffff0000, v106
	v_lshlrev_b32_e32 v70, 16, v107
	v_and_b32_e32 v71, 0xffff0000, v107
	v_pk_mul_f32 v[64:65], v[2:3], v[64:65] op_sel_hi:[0,1]
	v_pk_mul_f32 v[66:67], v[2:3], v[66:67] op_sel_hi:[0,1]
	v_pk_mul_f32 v[68:69], v[2:3], v[68:69] op_sel_hi:[0,1]
	v_pk_mul_f32 v[70:71], v[2:3], v[70:71] op_sel_hi:[0,1]
	v_pk_mul_f32 v[64:65], v[32:33], v[64:65]
	v_pk_mul_f32 v[66:67], v[34:35], v[66:67]
	v_pk_mul_f32 v[68:69], v[36:37], v[68:69]
	v_pk_mul_f32 v[70:71], v[38:39], v[70:71]
	global_store_dwordx4 v[8:9], v[64:67], off offset:0
	global_store_dwordx4 v[8:9], v[68:71], off offset:16
	v_lshlrev_b32_e32 v72, 16, v108
	v_and_b32_e32 v73, 0xffff0000, v108
	v_lshlrev_b32_e32 v74, 16, v109
	v_and_b32_e32 v75, 0xffff0000, v109
	v_lshlrev_b32_e32 v76, 16, v110
	v_and_b32_e32 v77, 0xffff0000, v110
	v_lshlrev_b32_e32 v78, 16, v111
	v_and_b32_e32 v79, 0xffff0000, v111
	v_pk_mul_f32 v[72:73], v[2:3], v[72:73] op_sel_hi:[0,1]
	v_pk_mul_f32 v[74:75], v[2:3], v[74:75] op_sel_hi:[0,1]
	v_pk_mul_f32 v[76:77], v[2:3], v[76:77] op_sel_hi:[0,1]
	v_pk_mul_f32 v[78:79], v[2:3], v[78:79] op_sel_hi:[0,1]
	v_pk_mul_f32 v[72:73], v[40:41], v[72:73]
	v_pk_mul_f32 v[74:75], v[42:43], v[74:75]
	v_pk_mul_f32 v[76:77], v[44:45], v[76:77]
	v_pk_mul_f32 v[78:79], v[46:47], v[78:79]
	global_store_dwordx4 v[8:9], v[72:75], off offset:2048
	global_store_dwordx4 v[8:9], v[76:79], off offset:2064
	v_lshl_add_u64 v[8:9], v[8:9], 0, s[20:21]
	s_add_u32 s10, s10, s23
	global_load_dword v145, v[6:7], off
	global_load_dwordx4 v[96:99], v[4:5], off
	global_load_dwordx4 v[100:103], v[4:5], off offset:1024
	global_load_dwordx4 v[104:107], v[4:5], off offset:2048
	global_load_dwordx4 v[108:111], v[4:5], off offset:3072
	v_lshl_add_u64 v[4:5], v[4:5], 0, s[12:13]
	v_lshl_add_u64 v[6:7], v[6:7], 0, s[18:19]
	s_cmp_lt_u32 s10, 0x10000
	s_cbranch_scc0 .Lfin_done
	s_waitcnt vmcnt(39)
	v_fmamk_f32 v2, v146, 0x3a000000, v14
	v_mul_f32_e32 v15, 0x4b800000, v2
	v_cmp_gt_f32_e32 vcc, s22, v2
	s_nop 1
	v_cndmask_b32_e32 v2, v2, v15, vcc
	v_rsq_f32_e32 v2, v2
	s_nop 0
	v_mul_f32_e32 v15, 0x45800000, v2
	v_cndmask_b32_e32 v2, v2, v15, vcc
	v_lshlrev_b32_e32 v48, 16, v112
	v_and_b32_e32 v49, 0xffff0000, v112
	v_lshlrev_b32_e32 v50, 16, v113
	v_and_b32_e32 v51, 0xffff0000, v113
	v_lshlrev_b32_e32 v52, 16, v114
	v_and_b32_e32 v53, 0xffff0000, v114
	v_lshlrev_b32_e32 v54, 16, v115
	v_and_b32_e32 v55, 0xffff0000, v115
	v_pk_mul_f32 v[48:49], v[2:3], v[48:49] op_sel_hi:[0,1]
	v_pk_mul_f32 v[50:51], v[2:3], v[50:51] op_sel_hi:[0,1]
	v_pk_mul_f32 v[52:53], v[2:3], v[52:53] op_sel_hi:[0,1]
	v_pk_mul_f32 v[54:55], v[2:3], v[54:55] op_sel_hi:[0,1]
	v_pk_mul_f32 v[48:49], v[16:17], v[48:49]
	v_pk_mul_f32 v[50:51], v[18:19], v[50:51]
	v_pk_mul_f32 v[52:53], v[20:21], v[52:53]
	v_pk_mul_f32 v[54:55], v[22:23], v[54:55]
	global_store_dwordx4 v[8:9], v[48:51], off offset:-4096
	global_store_dwordx4 v[8:9], v[52:55], off offset:-4080
	v_lshlrev_b32_e32 v56, 16, v116
	v_and_b32_e32 v57, 0xffff0000, v116
	v_lshlrev_b32_e32 v58, 16, v117
	v_and_b32_e32 v59, 0xffff0000, v117
	v_lshlrev_b32_e32 v60, 16, v118
	v_and_b32_e32 v61, 0xffff0000, v118
	v_lshlrev_b32_e32 v62, 16, v119
	v_and_b32_e32 v63, 0xffff0000, v119
	v_pk_mul_f32 v[56:57], v[2:3], v[56:57] op_sel_hi:[0,1]
	v_pk_mul_f32 v[58:59], v[2:3], v[58:59] op_sel_hi:[0,1]
	v_pk_mul_f32 v[60:61], v[2:3], v[60:61] op_sel_hi:[0,1]
	v_pk_mul_f32 v[62:63], v[2:3], v[62:63] op_sel_hi:[0,1]
	v_pk_mul_f32 v[56:57], v[24:25], v[56:57]
	v_pk_mul_f32 v[58:59], v[26:27], v[58:59]
	v_pk_mul_f32 v[60:61], v[28:29], v[60:61]
	v_pk_mul_f32 v[62:63], v[30:31], v[62:63]
	global_store_dwordx4 v[8:9], v[56:59], off offset:-2048
	global_store_dwordx4 v[8:9], v[60:63], off offset:-2032
	v_lshlrev_b32_e32 v64, 16, v120
	v_and_b32_e32 v65, 0xffff0000, v120
	v_lshlrev_b32_e32 v66, 16, v121
	v_and_b32_e32 v67, 0xffff0000, v121
	v_lshlrev_b32_e32 v68, 16, v122
	v_and_b32_e32 v69, 0xffff0000, v122
	v_lshlrev_b32_e32 v70, 16, v123
	v_and_b32_e32 v71, 0xffff0000, v123
	v_pk_mul_f32 v[64:65], v[2:3], v[64:65] op_sel_hi:[0,1]
	v_pk_mul_f32 v[66:67], v[2:3], v[66:67] op_sel_hi:[0,1]
	v_pk_mul_f32 v[68:69], v[2:3], v[68:69] op_sel_hi:[0,1]
	v_pk_mul_f32 v[70:71], v[2:3], v[70:71] op_sel_hi:[0,1]
	v_pk_mul_f32 v[64:65], v[32:33], v[64:65]
	v_pk_mul_f32 v[66:67], v[34:35], v[66:67]
	v_pk_mul_f32 v[68:69], v[36:37], v[68:69]
	v_pk_mul_f32 v[70:71], v[38:39], v[70:71]
	global_store_dwordx4 v[8:9], v[64:67], off offset:0
	global_store_dwordx4 v[8:9], v[68:71], off offset:16
	v_lshlrev_b32_e32 v72, 16, v124
	v_and_b32_e32 v73, 0xffff0000, v124
	v_lshlrev_b32_e32 v74, 16, v125
	v_and_b32_e32 v75, 0xffff0000, v125
	v_lshlrev_b32_e32 v76, 16, v126
	v_and_b32_e32 v77, 0xffff0000, v126
	v_lshlrev_b32_e32 v78, 16, v127
	v_and_b32_e32 v79, 0xffff0000, v127
	v_pk_mul_f32 v[72:73], v[2:3], v[72:73] op_sel_hi:[0,1]
	v_pk_mul_f32 v[74:75], v[2:3], v[74:75] op_sel_hi:[0,1]
	v_pk_mul_f32 v[76:77], v[2:3], v[76:77] op_sel_hi:[0,1]
	v_pk_mul_f32 v[78:79], v[2:3], v[78:79] op_sel_hi:[0,1]
	v_pk_mul_f32 v[72:73], v[40:41], v[72:73]
	v_pk_mul_f32 v[74:75], v[42:43], v[74:75]
	v_pk_mul_f32 v[76:77], v[44:45], v[76:77]
	v_pk_mul_f32 v[78:79], v[46:47], v[78:79]
	global_store_dwordx4 v[8:9], v[72:75], off offset:2048
	global_store_dwordx4 v[8:9], v[76:79], off offset:2064
	v_lshl_add_u64 v[8:9], v[8:9], 0, s[20:21]
	s_add_u32 s10, s10, s23
	global_load_dword v146, v[6:7], off
	global_load_dwordx4 v[112:115], v[4:5], off
	global_load_dwordx4 v[116:119], v[4:5], off offset:1024
	global_load_dwordx4 v[120:123], v[4:5], off offset:2048
	global_load_dwordx4 v[124:127], v[4:5], off offset:3072
	v_lshl_add_u64 v[4:5], v[4:5], 0, s[12:13]
	v_lshl_add_u64 v[6:7], v[6:7], 0, s[18:19]
	s_cmp_lt_u32 s10, 0x10000
	s_cbranch_scc0 .Lfin_done
	s_waitcnt vmcnt(39)
	v_fmamk_f32 v2, v147, 0x3a000000, v14
	v_mul_f32_e32 v15, 0x4b800000, v2
	v_cmp_gt_f32_e32 vcc, s22, v2
	s_nop 1
	v_cndmask_b32_e32 v2, v2, v15, vcc
	v_rsq_f32_e32 v2, v2
	s_nop 0
	v_mul_f32_e32 v15, 0x45800000, v2
	v_cndmask_b32_e32 v2, v2, v15, vcc
	v_lshlrev_b32_e32 v48, 16, v128
	v_and_b32_e32 v49, 0xffff0000, v128
	v_lshlrev_b32_e32 v50, 16, v129
	v_and_b32_e32 v51, 0xffff0000, v129
	v_lshlrev_b32_e32 v52, 16, v130
	v_and_b32_e32 v53, 0xffff0000, v130
	v_lshlrev_b32_e32 v54, 16, v131
	v_and_b32_e32 v55, 0xffff0000, v131
	v_pk_mul_f32 v[48:49], v[2:3], v[48:49] op_sel_hi:[0,1]
	v_pk_mul_f32 v[50:51], v[2:3], v[50:51] op_sel_hi:[0,1]
	v_pk_mul_f32 v[52:53], v[2:3], v[52:53] op_sel_hi:[0,1]
	v_pk_mul_f32 v[54:55], v[2:3], v[54:55] op_sel_hi:[0,1]
	v_pk_mul_f32 v[48:49], v[16:17], v[48:49]
	v_pk_mul_f32 v[50:51], v[18:19], v[50:51]
	v_pk_mul_f32 v[52:53], v[20:21], v[52:53]
	v_pk_mul_f32 v[54:55], v[22:23], v[54:55]
	global_store_dwordx4 v[8:9], v[48:51], off offset:-4096
	global_store_dwordx4 v[8:9], v[52:55], off offset:-4080
	v_lshlrev_b32_e32 v56, 16, v132
	v_and_b32_e32 v57, 0xffff0000, v132
	v_lshlrev_b32_e32 v58, 16, v133
	v_and_b32_e32 v59, 0xffff0000, v133
	v_lshlrev_b32_e32 v60, 16, v134
	v_and_b32_e32 v61, 0xffff0000, v134
	v_lshlrev_b32_e32 v62, 16, v135
	v_and_b32_e32 v63, 0xffff0000, v135
	v_pk_mul_f32 v[56:57], v[2:3], v[56:57] op_sel_hi:[0,1]
	v_pk_mul_f32 v[58:59], v[2:3], v[58:59] op_sel_hi:[0,1]
	v_pk_mul_f32 v[60:61], v[2:3], v[60:61] op_sel_hi:[0,1]
	v_pk_mul_f32 v[62:63], v[2:3], v[62:63] op_sel_hi:[0,1]
	v_pk_mul_f32 v[56:57], v[24:25], v[56:57]
	v_pk_mul_f32 v[58:59], v[26:27], v[58:59]
	v_pk_mul_f32 v[60:61], v[28:29], v[60:61]
	v_pk_mul_f32 v[62:63], v[30:31], v[62:63]
	global_store_dwordx4 v[8:9], v[56:59], off offset:-2048
	global_store_dwordx4 v[8:9], v[60:63], off offset:-2032
	v_lshlrev_b32_e32 v64, 16, v136
	v_and_b32_e32 v65, 0xffff0000, v136
	v_lshlrev_b32_e32 v66, 16, v137
	v_and_b32_e32 v67, 0xffff0000, v137
	v_lshlrev_b32_e32 v68, 16, v138
	v_and_b32_e32 v69, 0xffff0000, v138
	v_lshlrev_b32_e32 v70, 16, v139
	v_and_b32_e32 v71, 0xffff0000, v139
	v_pk_mul_f32 v[64:65], v[2:3], v[64:65] op_sel_hi:[0,1]
	v_pk_mul_f32 v[66:67], v[2:3], v[66:67] op_sel_hi:[0,1]
	v_pk_mul_f32 v[68:69], v[2:3], v[68:69] op_sel_hi:[0,1]
	v_pk_mul_f32 v[70:71], v[2:3], v[70:71] op_sel_hi:[0,1]
	v_pk_mul_f32 v[64:65], v[32:33], v[64:65]
	v_pk_mul_f32 v[66:67], v[34:35], v[66:67]
	v_pk_mul_f32 v[68:69], v[36:37], v[68:69]
	v_pk_mul_f32 v[70:71], v[38:39], v[70:71]
	global_store_dwordx4 v[8:9], v[64:67], off offset:0
	global_store_dwordx4 v[8:9], v[68:71], off offset:16
	v_lshlrev_b32_e32 v72, 16, v140
	v_and_b32_e32 v73, 0xffff0000, v140
	v_lshlrev_b32_e32 v74, 16, v141
	v_and_b32_e32 v75, 0xffff0000, v141
	v_lshlrev_b32_e32 v76, 16, v142
	v_and_b32_e32 v77, 0xffff0000, v142
	v_lshlrev_b32_e32 v78, 16, v143
	v_and_b32_e32 v79, 0xffff0000, v143
	v_pk_mul_f32 v[72:73], v[2:3], v[72:73] op_sel_hi:[0,1]
	v_pk_mul_f32 v[74:75], v[2:3], v[74:75] op_sel_hi:[0,1]
	v_pk_mul_f32 v[76:77], v[2:3], v[76:77] op_sel_hi:[0,1]
	v_pk_mul_f32 v[78:79], v[2:3], v[78:79] op_sel_hi:[0,1]
	v_pk_mul_f32 v[72:73], v[40:41], v[72:73]
	v_pk_mul_f32 v[74:75], v[42:43], v[74:75]
	v_pk_mul_f32 v[76:77], v[44:45], v[76:77]
	v_pk_mul_f32 v[78:79], v[46:47], v[78:79]
	global_store_dwordx4 v[8:9], v[72:75], off offset:2048
	global_store_dwordx4 v[8:9], v[76:79], off offset:2064
	v_lshl_add_u64 v[8:9], v[8:9], 0, s[20:21]
	s_add_u32 s10, s10, s23
	global_load_dword v147, v[6:7], off
	global_load_dwordx4 v[128:131], v[4:5], off
	global_load_dwordx4 v[132:135], v[4:5], off offset:1024
	global_load_dwordx4 v[136:139], v[4:5], off offset:2048
	global_load_dwordx4 v[140:143], v[4:5], off offset:3072
	v_lshl_add_u64 v[4:5], v[4:5], 0, s[12:13]
	v_lshl_add_u64 v[6:7], v[6:7], 0, s[18:19]
	s_branch .Lfin_loop
.Lfin_done:
	s_waitcnt vmcnt(0)
.LBB0_875:
	s_endpgm

	.amdhsa_kernel _Z4mega6Params
		.amdhsa_group_segment_fixed_size 0
		.amdhsa_private_segment_fixed_size 0
		.amdhsa_kernarg_size 416
		.amdhsa_user_sgpr_count 2
		.amdhsa_user_sgpr_dispatch_ptr 0
		.amdhsa_user_sgpr_queue_ptr 0
		.amdhsa_user_sgpr_kernarg_segment_ptr 1
		.amdhsa_user_sgpr_dispatch_id 0
		.amdhsa_user_sgpr_kernarg_preload_length 0
		.amdhsa_user_sgpr_kernarg_preload_offset 0
		.amdhsa_user_sgpr_private_segment_size 0
		.amdhsa_uses_dynamic_stack 0
		.amdhsa_enable_private_segment 0
		.amdhsa_system_sgpr_workgroup_id_x 1
		.amdhsa_system_sgpr_workgroup_id_y 0
		.amdhsa_system_sgpr_workgroup_id_z 0
		.amdhsa_system_sgpr_workgroup_info 0
		.amdhsa_system_vgpr_workitem_id 2
		.amdhsa_next_free_vgpr 252
		.amdhsa_next_free_sgpr 102
		.amdhsa_accum_offset 252
		.amdhsa_reserve_vcc 1
		.amdhsa_float_round_mode_32 0
		.amdhsa_float_round_mode_16_64 0
		.amdhsa_float_denorm_mode_32 3
		.amdhsa_float_denorm_mode_16_64 3
		.amdhsa_dx10_clamp 1
		.amdhsa_ieee_mode 1
		.amdhsa_fp16_overflow 0
		.amdhsa_tg_split 0
		.amdhsa_exception_fp_ieee_invalid_op 0
		.amdhsa_exception_fp_denorm_src 0
		.amdhsa_exception_fp_ieee_div_zero 0
		.amdhsa_exception_fp_ieee_overflow 0
		.amdhsa_exception_fp_ieee_underflow 0
		.amdhsa_exception_fp_ieee_inexact 0
		.amdhsa_exception_int_div_zero 0
	.end_amdhsa_kernel

amdhsa.kernels:
  - .agpr_count:     0
    .args:
      - .offset:         0
        .size:           160
        .value_kind:     by_value
      - .offset:         160
        .size:           4
        .value_kind:     hidden_block_count_x
      - .offset:         164
        .size:           4
        .value_kind:     hidden_block_count_y
      - .offset:         168
        .size:           4
        .value_kind:     hidden_block_count_z
      - .offset:         172
        .size:           2
        .value_kind:     hidden_group_size_x
      - .offset:         174
        .size:           2
        .value_kind:     hidden_group_size_y
      - .offset:         176
        .size:           2
        .value_kind:     hidden_group_size_z
      - .offset:         178
        .size:           2
        .value_kind:     hidden_remainder_x
      - .offset:         180
        .size:           2
        .value_kind:     hidden_remainder_y
      - .offset:         182
        .size:           2
        .value_kind:     hidden_remainder_z
      - .offset:         200
        .size:           8
        .value_kind:     hidden_global_offset_x
      - .offset:         208
        .size:           8
        .value_kind:     hidden_global_offset_y
      - .offset:         216
        .size:           8
        .value_kind:     hidden_global_offset_z
      - .offset:         224
        .size:           2
        .value_kind:     hidden_grid_dims
      - .offset:         248
        .size:           8
        .value_kind:     hidden_multigrid_sync_arg
      - .offset:         280
        .size:           4
        .value_kind:     hidden_dynamic_lds_size
    .group_segment_fixed_size: 0
    .kernarg_segment_align: 8
    .kernarg_segment_size: 416
    .language:       OpenCL C
    .language_version:
      - 2
      - 0
    .max_flat_workgroup_size: 512
    .name:           _Z4mega6Params
    .private_segment_fixed_size: 0
    .sgpr_count:     108
    .sgpr_spill_count: 83
    .symbol:         _Z4mega6Params.kd
    .uniform_work_group_size: 1
    .uses_dynamic_stack: false
    .vgpr_count:     252
    .vgpr_spill_count: 0
    .wavefront_size: 64
